# final-PV LDS reads double-buffered in all three attention modes; mode-0 unit prologue bias-table load overlapped with Q/K/V loads (counted vmcnt)
# speedup vs baseline: 1.0026x; 1.0002x over previous
; #define GAS __attribute__((address_space(1)))
; __device__ __forceinline__ float swapsum(float m) { auto rr = __builtin_amdgcn_permlane32_swap(__float_as_uint(m), __float_as_uint(m), false, false); return __uint_as_float(rr[0]) + __uint_as_float(rr[1]); }
; __device__ __forceinline__ unsigned cvtpk(float lo, float hi) { f32x2_t v = {lo, hi}; bf16x2_t b = __builtin_convertvector(v, bf16x2_t); return __builtin_bit_cast(unsigned, b); }
; template <int MODE> __device__ __forceinline__ void attn_unit4(LAS unsigned char* lds, const int uidx, const AttnArgs& A) {
;     ...
;     __builtin_amdgcn_s_setprio(0);
;     A2_PV(vs_prev, pk);
;     __syncthreads();
;     ...
;     float lt = swapsum(lsum);
;     if (MODE == 2) lt += __builtin_amdgcn_exp2f(A.sinks[2 * hx + st] * LOG2E - mref);
;     const float inv = 1.0f / lt;
; #pragma unroll
;     for (int d = 0; d < NDB; ++d)
; #pragma unroll
;         for (int r = 0; r < 16; ++r) o[d][r] *= inv;
;     ...
;     } else {
;         GAS bf16_t* op = (GAS bf16_t*)A.O + orow * DM + (MODE == 1 ? 768 : 512) + (2 * hx + st) * 64 + 4 * hi;
; #pragma unroll
;         for (int d = 0; d < NDB; ++d)
; #pragma unroll
;             for (int g4 = 0; g4 < 4; ++g4) {
;                 u32x2 w; w.x = cvtpk(o[d][4 * g4], o[d][4 * g4 + 1]); w.y = cvtpk(o[d][4 * g4 + 2], o[d][4 * g4 + 3]);
;                 *(GAS u32x2*)(op + d * 32 + 8 * g4) = w;
;             }
;     }
;     __syncthreads();
.Lpf_m2:
	s_mov_b64 exec, s[76:77]
	v_mov_b32_e32 v131, v1
	s_setprio 0
	s_mul_i32 s5, s26, 0x5000
	s_add_i32 s5, s5, 0
	v_add_u32_e32 v0, s5, v141
	ds_read_b64_tr_b16 v[34:35], v0 offset:51200
	ds_read_b64_tr_b16 v[36:37], v0 offset:53760
	v_add_u32_e32 v38, 0xc800, v0
	s_ashr_i32 s5, s4, 31
	s_lshl_b64 s[4:5], s[4:5], 2
	s_add_u32 s4, s68, s4
	ds_read_b64_tr_b16 v[244:245], v0 offset:56320
	ds_read_b64_tr_b16 v[246:247], v0 offset:58880
	s_addc_u32 s5, s89, s5
	s_waitcnt lgkmcnt(2)
	v_mfma_f32_32x32x16_bf16 v[2:17], v[34:37], v[102:105], v[2:17]
	ds_read_b64_tr_b16 v[34:35], v0 offset:61440
	ds_read_b64_tr_b16 v[36:37], v0 offset:64000
	s_waitcnt lgkmcnt(2)
	v_mfma_f32_32x32x16_bf16 v[2:17], v[244:247], v[98:101], v[2:17]
	ds_read_b64_tr_b16 v[244:245], v38 offset:15360
	ds_read_b64_tr_b16 v[246:247], v38 offset:17920
	s_waitcnt lgkmcnt(2)
	v_mfma_f32_32x32x16_bf16 v[2:17], v[34:37], v[110:113], v[2:17]
	ds_read_b64_tr_b16 v[34:35], v0 offset:51264
	ds_read_b64_tr_b16 v[36:37], v0 offset:53824
	s_waitcnt lgkmcnt(2)
	v_mfma_f32_32x32x16_bf16 v[2:17], v[244:247], v[106:109], v[2:17]
	ds_read_b64_tr_b16 v[244:245], v0 offset:56384
	ds_read_b64_tr_b16 v[246:247], v0 offset:58944
	s_waitcnt lgkmcnt(2)
	v_mfma_f32_32x32x16_bf16 v[18:33], v[34:37], v[102:105], v[18:33]
	ds_read_b64_tr_b16 v[34:35], v0 offset:61504
	ds_read_b64_tr_b16 v[36:37], v0 offset:64064
	v_mov_b32_e32 v0, v160
	s_nop 1
	v_permlane32_swap_b32_e32 v160, v0
	v_add_f32_e32 v0, v160, v0
	s_waitcnt lgkmcnt(2)
	v_mfma_f32_32x32x16_bf16 v[18:33], v[244:247], v[98:101], v[18:33]
	ds_read_b64_tr_b16 v[244:245], v38 offset:15424
	ds_read_b64_tr_b16 v[246:247], v38 offset:17984
	s_waitcnt lgkmcnt(2)
	v_mfma_f32_32x32x16_bf16 v[18:33], v[34:37], v[110:113], v[18:33]
	s_waitcnt lgkmcnt(0)
	s_barrier
	v_mfma_f32_32x32x16_bf16 v[18:33], v[244:247], v[106:109], v[18:33]
	global_load_dword v34, v1, s[4:5]
	s_mov_b32 s4, 0x3fb8aa3b
	s_waitcnt vmcnt(0)
	v_fma_f32 v34, v34, s4, -v143
	v_exp_f32_e32 v34, v34
	s_nop 0
	v_add_f32_e32 v0, v0, v34
	v_div_scale_f32 v34, s[4:5], v0, v0, 1.0
	v_rcp_f32_e32 v35, v34
	s_nop 0
	v_fma_f32 v36, -v34, v35, 1.0
	v_fmac_f32_e32 v35, v36, v35
	v_div_scale_f32 v36, vcc, 1.0, v0, 1.0
	v_mul_f32_e32 v37, v36, v35
	v_fma_f32 v38, -v34, v37, v36
	v_fmac_f32_e32 v37, v38, v35
	v_fma_f32 v34, -v34, v37, v36
	v_div_fmas_f32 v34, v34, v35, v37
	v_div_fixup_f32 v0, v34, v0, 1.0
	v_pk_mul_f32 v[34:35], v[14:15], v[0:1] op_sel_hi:[1,0]
	v_pk_mul_f32 v[14:15], v[18:19], v[0:1] op_sel_hi:[1,0]
	v_lshlrev_b64 v[18:19], 11, v[130:131]
	v_lshl_add_u64 v[18:19], s[10:11], 0, v[18:19]
	v_pk_mul_f32 v[46:47], v[2:3], v[0:1] op_sel_hi:[1,0]
	v_pk_mul_f32 v[48:49], v[4:5], v[0:1] op_sel_hi:[1,0]
	v_pk_mul_f32 v[42:43], v[6:7], v[0:1] op_sel_hi:[1,0]
	v_pk_mul_f32 v[44:45], v[8:9], v[0:1] op_sel_hi:[1,0]
	v_pk_mul_f32 v[38:39], v[10:11], v[0:1] op_sel_hi:[1,0]
	v_pk_mul_f32 v[40:41], v[12:13], v[0:1] op_sel_hi:[1,0]
	v_pk_mul_f32 v[36:37], v[16:17], v[0:1] op_sel_hi:[1,0]
	v_pk_mul_f32 v[16:17], v[20:21], v[0:1] op_sel_hi:[1,0]
	v_pk_mul_f32 v[10:11], v[22:23], v[0:1] op_sel_hi:[1,0]
	v_pk_mul_f32 v[12:13], v[24:25], v[0:1] op_sel_hi:[1,0]
	v_pk_mul_f32 v[6:7], v[26:27], v[0:1] op_sel_hi:[1,0]
	v_pk_mul_f32 v[8:9], v[28:29], v[0:1] op_sel_hi:[1,0]
	v_pk_mul_f32 v[2:3], v[30:31], v[0:1] op_sel_hi:[1,0]
	v_pk_mul_f32 v[4:5], v[32:33], v[0:1] op_sel_hi:[1,0]
	v_lshl_add_u64 v[18:19], s[0:1], 1, v[18:19]
	v_lshlrev_b32_e32 v0, 1, v133
	v_lshl_add_u64 v[18:19], v[18:19], 0, v[0:1]
	v_cvt_pk_bf16_f32 v20, v46, v47
	v_cvt_pk_bf16_f32 v21, v48, v49
	global_store_dwordx2 v[18:19], v[20:21], off offset:1024
	v_cvt_pk_bf16_f32 v20, v42, v43
	v_cvt_pk_bf16_f32 v21, v44, v45
	global_store_dwordx2 v[18:19], v[20:21], off offset:1040
	v_cvt_pk_bf16_f32 v20, v38, v39
	v_cvt_pk_bf16_f32 v21, v40, v41
	global_store_dwordx2 v[18:19], v[20:21], off offset:1056
	v_cvt_pk_bf16_f32 v20, v34, v35
	v_cvt_pk_bf16_f32 v21, v36, v37
	v_cvt_pk_bf16_f32 v14, v14, v15
	v_cvt_pk_bf16_f32 v15, v16, v17
	v_cvt_pk_bf16_f32 v10, v10, v11
	v_cvt_pk_bf16_f32 v11, v12, v13
	v_cvt_pk_bf16_f32 v6, v6, v7
	v_cvt_pk_bf16_f32 v7, v8, v9
	v_cvt_pk_bf16_f32 v2, v2, v3
	v_cvt_pk_bf16_f32 v3, v4, v5
	global_store_dwordx2 v[18:19], v[20:21], off offset:1072
	global_store_dwordx2 v[18:19], v[14:15], off offset:1088
	global_store_dwordx2 v[18:19], v[10:11], off offset:1104
	global_store_dwordx2 v[18:19], v[6:7], off offset:1120
	global_store_dwordx2 v[18:19], v[2:3], off offset:1136
	s_barrier
	s_mov_b64 s[0:1], 0

; #define LAS __attribute__((address_space(3)))
; #define GAS __attribute__((address_space(1)))
; template <int MODE> __device__ __forceinline__ void attn_unit4(LAS unsigned char* lds, const int uidx, const AttnArgs& A) {
;     ...
;     if (MODE != 1) {
;         const int rel = tid - 256; const int bk = t5_bucket_dev(rel);
;         if (MODE == 0) { tab[tid] = A.rel_bias[bk * 8 + hx] * LOG2E; }
;         else { const bool okw = (rel <= 128 && rel >= -128);
;             tab[tid] = okw ? A.rel_bias[bk * 8 + 4 + 2 * hx] * LOG2E : negbig; tab[512 + tid] = okw ? A.rel_bias[bk * 8 + 4 + 2 * hx + 1] * LOG2E : negbig; }
;     }
;     const int qslot0 = qb * 128 + qg * 32;
;     bf16x8 qf[NKC];
;     { const GAS bf16_t* qp = Qg + (row0 + qslot0 + r32) * DIN + hi * 8;
; #pragma unroll
;       for (int kc = 0; kc < NKC; ++kc) qf[kc] = *(const GAS bf16x8*)(qp + kc * 16); }
;     int ksrc[NKL], kdst[NKL], vsrc[NVL], vdst[NVL];
; #pragma unroll
;     for (int i = 0; i < NKL; ++i) { const int id = tid + NTHR * i, key = id / KCH, ch = id % KCH; ksrc[i] = key * kld + ch * 8; kdst[i] = key * KSTR + ch * 16; }
; #pragma unroll
;     for (int i = 0; i < NVL; ++i) { const int id = tid + NTHR * i, key = id / VCH, ch = id % VCH; vsrc[i] = key * vld + ch * 8; vdst[i] = VBASE + key * VSTR + ch * 16; }
;     u32x4 kst[NKL], vst[NVL];
;     ...
;     f32x16 o[NDB];
; #pragma unroll
;     for (int d = 0; d < NDB; ++d)
; #pragma unroll
;         for (int r = 0; r < 16; ++r) o[d][r] = 0.f;
;     float lsum = 0.f;
;     const int kfrag = st * KSOFF + r32 * KSTR + hi * 16;
;     const int vfrag = st * VSOFF + (4 * hi + ((lane & 15) >> 2)) * VSTR + ((lane >> 4) & 1) * 32 + (lane & 3) * 8;
;     const LAS float* mytab = tab + (MODE == 2 ? st * 512 : 0);
;     {
;       u32x4 kst2[NKL];
;       A2_ISSUE_K(t0); A2_ISSUE_V(t0);
;       { const GAS bf16_t* kp_ = Kg + (row0 + 64 * (size_t)(t0 + 1)) * kld;
; #pragma unroll
;         for (int i = 0; i < NKL; ++i) kst2[i] = *(const GAS u32x4*)(kp_ + ksrc[i]); }
;       A2_COMMIT_K(t0 & 1); A2_COMMIT_V(0);
;       { LAS unsigned char* bb_ = lds + ((t0 + 1) & 1) * KSTG;
; #pragma unroll
;         for (int i = 0; i < NKL; ++i) *(LAS u32x4*)(bb_ + kdst[i]) = kst2[i]; } }
;     __syncthreads();
;     ...
;     A2_TILE_BIAS(t0, cbc, nearc);
;     { const float zero_ = 0.f; A2_QK(s0, s1, t0 & 1, zero_); }
;     __syncthreads();
;     if (MODE != 1 && nearc) A4_BIAS(t0, s0, s1);
.LBB0_979:
	s_or_b64 exec, exec, s[0:1]
	s_ashr_i32 s0, s53, 7
	s_add_i32 s4, s0, s64
	s_lshr_b32 s0, s37, 30
	s_movk_i32 s6, 0x100
	s_add_i32 s0, s37, s0
	v_cmp_lt_i32_e32 vcc, s6, v19
	s_and_b32 s0, s0, -4
	s_sub_i32 s5, s37, s0
	v_cndmask_b32_e64 v2, 0, 16, vcc
	v_add_u32_e32 v0, v0, v2
	v_lshl_add_u32 v2, v0, 3, s5
	v_readlane_b32 s6, v254, 15
	v_ashrrev_i32_e32 v3, 31, v2
	v_readlane_b32 s7, v254, 16
	s_lshl_b32 s26, s5, 7
	s_ashr_i32 s70, s30, 6
	v_lshl_add_u64 v[2:3], v[2:3], 2, s[6:7]
	global_load_dword v248, v[2:3], off
	s_ashr_i32 s27, s26, 31
	s_and_b32 s65, s70, 3
	s_ashr_i32 s69, s30, 8
	s_lshl_b64 s[8:9], s[26:27], 1
	s_add_u32 s39, s16, s8
	s_addc_u32 s40, s17, s9
	s_lshl_b32 s0, s69, 6
	s_ashr_i32 s1, s0, 31
	s_lshl_b64 s[0:1], s[0:1], 1
	s_add_u32 s0, s39, s0
	s_addc_u32 s1, s40, s1
	s_lshl_b32 s5, s52, 7
	s_lshl_b32 s52, s65, 5
	s_or_b32 s71, s52, s5
	s_mul_i32 s38, s4, 0x2080
	s_add_i32 s15, 0, 0x1b800
	s_ashr_i32 s5, s71, 31
	v_and_b32_e32 v21, 31, v19
	v_lshl_add_u32 v247, v19, 2, s15
	s_add_u32 s6, s38, s71
	s_mul_hi_i32 s63, s4, 0x2080
	v_or_b32_e32 v166, s6, v21
	v_bfe_u32 v4, v19, 5, 1
	s_addc_u32 s5, s63, s5
	v_mov_b32_e32 v167, s5
	s_mul_i32 s73, s4, 0x271a000
	s_movk_i32 s6, 0x110
	s_mul_hi_i32 s53, s4, 0x271a000
	s_add_u32 s62, s39, s73
	s_addc_u32 s64, s40, s53
	v_lshlrev_b32_e32 v181, 2, v4
	v_mul_u32_u24_e32 v24, 0x110, v21
	v_mov_b32_e32 v23, s15
	v_mov_b64_e32 v[2:3], s[0:1]
	v_mad_u64_u32 v[2:3], s[0:1], v166, s45, v[2:3]
	v_mov_b32_e32 v0, 0x1340
	v_mad_i32_i24 v3, s5, v0, v3
	v_lshlrev_b32_e32 v0, 4, v4
	v_lshl_add_u64 v[2:3], v[2:3], 0, v[0:1]
	global_load_dwordx4 v[114:117], v[2:3], off
	global_load_dwordx4 v[118:121], v[2:3], off offset:32
	global_load_dwordx4 v[122:125], v[2:3], off offset:64
	global_load_dwordx4 v[126:129], v[2:3], off offset:96
	v_ashrrev_i32_e32 v2, 31, v19
	v_lshrrev_b32_e32 v2, 28, v2
	v_add_u32_e32 v2, v19, v2
	v_ashrrev_i32_e32 v33, 4, v2
	v_and_b32_e32 v2, -16, v2
	s_movk_i32 s5, 0x9a0
	v_sub_u32_e32 v2, v19, v2
	v_mul_lo_u32 v3, v33, s5
	v_lshl_add_u32 v172, v2, 3, v3
	v_lshlrev_b32_e32 v32, 4, v2
	v_add_u32_e32 v2, 0x200, v19
	v_ashrrev_i32_e32 v3, 31, v2
	v_lshrrev_b32_e32 v3, 28, v3
	v_add_u32_e32 v3, v2, v3
	v_ashrrev_i32_e32 v22, 4, v3
	v_and_b32_e32 v3, -16, v3
	v_sub_u32_e32 v2, v2, v3
	v_mul_lo_u32 v3, v22, s5
	v_mad_u64_u32 v[34:35], s[0:1], v33, s6, v[32:33]
	v_lshl_add_u32 v174, v2, 3, v3
	s_add_u32 s0, s62, 0x4d400
	v_ashrrev_i32_e32 v173, 31, v172
	v_ashrrev_i32_e32 v175, 31, v174
	s_addc_u32 s1, s64, 0
	v_lshlrev_b64 v[168:169], 1, v[172:173]
	v_lshlrev_b64 v[170:171], 1, v[174:175]
	s_lshl_b32 s4, s69, 7
	v_lshlrev_b32_e32 v20, 4, v2
	v_lshl_add_u64 v[2:3], s[0:1], 0, v[168:169]
	v_lshl_add_u64 v[6:7], s[0:1], 0, v[170:171]
	s_add_u32 s0, s62, 0x4d800
	s_addc_u32 s1, s64, 0
	s_add_u32 s41, s62, 0x400
	s_addc_u32 s14, s64, 0
	global_load_dwordx4 v[2:5], v[2:3], off
	v_lshl_add_u64 v[10:11], s[0:1], 0, v[168:169]
	v_lshl_add_u64 v[14:15], s[0:1], 0, v[170:171]
	s_add_u32 s0, s62, 0x9a400
	s_addc_u32 s1, s64, 0
	global_load_dwordx4 v[6:9], v[6:7], off
	v_add3_u32 v0, v0, v24, s4
	global_load_dwordx4 v[10:13], v[10:11], off
	v_lshl_add_u64 v[24:25], s[0:1], 0, v[168:169]
	global_load_dwordx4 v[14:17], v[14:15], off
	v_lshl_add_u64 v[28:29], s[0:1], 0, v[170:171]
	global_load_dwordx4 v[24:27], v[24:25], off
	s_movk_i32 s0, 0x140
	global_load_dwordx4 v[28:31], v[28:29], off
	v_mul_lo_u32 v35, v22, s6
	v_add_u32_e32 v190, 0, v34
	v_mad_u64_u32 v[176:177], s[0:1], v33, s0, v[32:33]
	v_add3_u32 v188, v35, v20, 0
	v_readlane_b32 s0, v254, 12
	v_add_u32_e32 v187, 0, v176
	v_add_u32_e32 v196, 0, v0
	s_waitcnt vmcnt(10)
	v_mul_f32_e32 v248, 0x3fb8aa3b, v248
	ds_write_b32 v247, v248
	s_waitcnt vmcnt(5)
	ds_write_b128 v190, v[2:5] offset:25600
	v_mul_lo_u32 v2, v22, 48
	v_add_u32_e32 v186, v188, v2
	v_mov_b32_e32 v2, s0
	s_add_i32 s0, s71, 57
	s_waitcnt vmcnt(4)
	ds_write_b128 v188, v[6:9] offset:25600
	s_cmpk_gt_u32 s0, 0x112
	s_waitcnt vmcnt(3)
	ds_write_b128 v187, v[10:13] offset:51200
	s_waitcnt vmcnt(2)
	ds_write_b128 v186, v[14:17] offset:51200
	s_waitcnt vmcnt(1)
	ds_write_b128 v190, v[24:27]
	s_waitcnt vmcnt(0)
	ds_write_b128 v188, v[28:31]
	s_waitcnt lgkmcnt(0)
	s_barrier
	ds_read_b32 v194, v23
	ds_read_b32 v195, v2
	ds_read_b128 v[2:5], v196 offset:34304
	ds_read_b128 v[24:27], v196 offset:34336
	s_waitcnt lgkmcnt(1)
	v_mfma_f32_32x32x16_bf16 v[2:17], v[2:5], v[114:117], 0
	s_waitcnt lgkmcnt(0)
	v_mfma_f32_32x32x16_bf16 v[2:17], v[24:27], v[118:121], v[2:17]
	ds_read_b128 v[24:27], v196 offset:34368
	s_waitcnt lgkmcnt(0)
	v_mfma_f32_32x32x16_bf16 v[2:17], v[24:27], v[122:125], v[2:17]
	ds_read_b128 v[24:27], v196 offset:34400
	s_waitcnt lgkmcnt(0)
	s_barrier
	v_mfma_f32_32x32x16_bf16 v[2:17], v[24:27], v[126:129], v[2:17]
	s_cbranch_scc1 .LBB0_981
	v_or_b32_e32 v0, 0x140, v181
	s_nop 9
	v_or_b32_e32 v2, s71, v21
	v_sub_u32_e32 v0, v0, v2
	v_mov_b32_e32 v2, 0x1cf
	s_movk_i32 s0, 0xffd0
	v_med3_i32 v2, v0, s0, v2
	v_lshl_add_u32 v8, v2, 2, s15
	v_mov_b32_e32 v2, 0x1ce
	s_movk_i32 s0, 0xffcf
	v_med3_i32 v2, v0, s0, v2
	v_lshl_add_u32 v9, v2, 2, s15
	v_mov_b32_e32 v2, 0x1cd
	s_movk_i32 s0, 0xffce
	v_med3_i32 v2, v0, s0, v2
	v_mov_b32_e32 v3, 0x1cc
	s_movk_i32 s0, 0xffcd
	v_med3_i32 v3, v0, s0, v3
	v_mov_b32_e32 v4, 0x1c7
	s_movk_i32 s0, 0xffc8
	v_med3_i32 v4, v0, s0, v4
	v_mov_b32_e32 v5, 0x1c6
	s_movk_i32 s0, 0xffc7
	v_med3_i32 v5, v0, s0, v5
	v_mov_b32_e32 v6, 0x1c5
	s_movk_i32 s0, 0xffc6
	v_med3_i32 v6, v0, s0, v6
	v_mov_b32_e32 v7, 0x1c4
	s_movk_i32 s0, 0xffc5
	v_lshl_add_u32 v2, v2, 2, s15
	v_lshl_add_u32 v3, v3, 2, s15
	v_lshl_add_u32 v4, v4, 2, s15
	v_lshl_add_u32 v5, v5, 2, s15
	v_lshl_add_u32 v6, v6, 2, s15
	v_med3_i32 v0, v0, s0, v7
	v_lshl_add_u32 v0, v0, 2, s15
	ds_read_b32 v2, v2 offset:200
	ds_read_b32 v3, v3 offset:204
	ds_read_b32 v4, v4 offset:224
	ds_read_b32 v6, v6 offset:232
	ds_read_b32 v7, v0 offset:236
	ds_read_b32 v5, v5 offset:228
	ds_read_b32 v8, v8 offset:192
	ds_read_b32 v9, v9 offset:196
	s_waitcnt lgkmcnt(6)
	v_pk_add_f32 v[12:13], v[12:13], v[2:3]
	s_waitcnt lgkmcnt(3)
	v_pk_add_f32 v[16:17], v[16:17], v[6:7]
	s_waitcnt lgkmcnt(2)
	v_pk_add_f32 v[14:15], v[14:15], v[4:5]
	s_waitcnt lgkmcnt(0)
	v_pk_add_f32 v[10:11], v[10:11], v[8:9]

; template <int MODE> __device__ __forceinline__ void attn_unit4(LAS unsigned char* lds, const int uidx, const AttnArgs& A) {
;     ...
;     if (__any(fprev != 1.0f)) {
; #pragma unroll
;         for (int d = 0; d < NDB; ++d)
; #pragma unroll
;             for (int r = 0; r < 16; ++r) o[d][r] *= fprev;
;     }
;     __builtin_amdgcn_s_setprio(0);
;     A2_PV(vs_prev, pk);
.Lpf_m0:
	s_mov_b64 exec, s[76:77]
	v_fmac_f32_e32 v0, v163, v162
	s_setprio 0
	v_add_u32_e32 v78, 0x16800, v192
	ds_read_b64_tr_b16 v[74:75], v78
	ds_read_b64_tr_b16 v[76:77], v78 offset:2560
	s_cmp_lg_u32 s69, 1
	ds_read_b64_tr_b16 v[244:245], v78 offset:5120
	ds_read_b64_tr_b16 v[246:247], v78 offset:7680
	s_waitcnt lgkmcnt(2)
	v_mfma_f32_32x32x16_bf16 v[50:65], v[74:77], v[82:85], v[50:65]
	ds_read_b64_tr_b16 v[74:75], v78 offset:10240
	ds_read_b64_tr_b16 v[76:77], v78 offset:12800
	s_waitcnt lgkmcnt(2)
	v_mfma_f32_32x32x16_bf16 v[50:65], v[244:247], v[86:89], v[50:65]
	ds_read_b64_tr_b16 v[244:245], v78 offset:15360
	ds_read_b64_tr_b16 v[246:247], v78 offset:17920
	s_waitcnt lgkmcnt(2)
	v_mfma_f32_32x32x16_bf16 v[50:65], v[74:77], v[66:69], v[50:65]
	ds_read_b64_tr_b16 v[74:75], v78 offset:64
	ds_read_b64_tr_b16 v[76:77], v78 offset:2624
	s_waitcnt lgkmcnt(2)
	v_mfma_f32_32x32x16_bf16 v[50:65], v[244:247], v[70:73], v[50:65]
	ds_read_b64_tr_b16 v[244:245], v78 offset:5184
	ds_read_b64_tr_b16 v[246:247], v78 offset:7744
	s_waitcnt lgkmcnt(2)
	v_mfma_f32_32x32x16_bf16 v[34:49], v[74:77], v[82:85], v[34:49]
	ds_read_b64_tr_b16 v[74:75], v78 offset:10304
	ds_read_b64_tr_b16 v[76:77], v78 offset:12864
	s_waitcnt lgkmcnt(2)
	v_mfma_f32_32x32x16_bf16 v[34:49], v[244:247], v[86:89], v[34:49]
	ds_read_b64_tr_b16 v[244:245], v78 offset:15424
	ds_read_b64_tr_b16 v[246:247], v78 offset:17984
	s_waitcnt lgkmcnt(2)
	v_mfma_f32_32x32x16_bf16 v[34:49], v[74:77], v[66:69], v[34:49]
	ds_read_b64_tr_b16 v[74:75], v78 offset:128
	ds_read_b64_tr_b16 v[76:77], v78 offset:2688
	s_waitcnt lgkmcnt(2)
	v_mfma_f32_32x32x16_bf16 v[34:49], v[244:247], v[70:73], v[34:49]
	ds_read_b64_tr_b16 v[244:245], v78 offset:5248
	ds_read_b64_tr_b16 v[246:247], v78 offset:7808
	s_waitcnt lgkmcnt(2)
	v_mfma_f32_32x32x16_bf16 v[18:33], v[74:77], v[82:85], v[18:33]
	ds_read_b64_tr_b16 v[74:75], v78 offset:10368
	ds_read_b64_tr_b16 v[76:77], v78 offset:12928
	s_waitcnt lgkmcnt(2)
	v_mfma_f32_32x32x16_bf16 v[18:33], v[244:247], v[86:89], v[18:33]
	ds_read_b64_tr_b16 v[244:245], v78 offset:15488
	ds_read_b64_tr_b16 v[246:247], v78 offset:18048
	s_waitcnt lgkmcnt(2)
	v_mfma_f32_32x32x16_bf16 v[18:33], v[74:77], v[66:69], v[18:33]
	ds_read_b64_tr_b16 v[74:75], v78 offset:192
	ds_read_b64_tr_b16 v[76:77], v78 offset:2752
	s_waitcnt lgkmcnt(2)
	v_mfma_f32_32x32x16_bf16 v[18:33], v[244:247], v[70:73], v[18:33]
	ds_read_b64_tr_b16 v[244:245], v78 offset:5312
	ds_read_b64_tr_b16 v[246:247], v78 offset:7872
	s_waitcnt lgkmcnt(2)
	v_mfma_f32_32x32x16_bf16 v[2:17], v[74:77], v[82:85], v[2:17]
	ds_read_b64_tr_b16 v[74:75], v78 offset:10432
	ds_read_b64_tr_b16 v[76:77], v78 offset:12992
	s_waitcnt lgkmcnt(2)
	v_mfma_f32_32x32x16_bf16 v[2:17], v[244:247], v[86:89], v[2:17]
	ds_read_b64_tr_b16 v[244:245], v78 offset:15552
	ds_read_b64_tr_b16 v[246:247], v78 offset:18112
	s_waitcnt lgkmcnt(2)
	v_mfma_f32_32x32x16_bf16 v[2:17], v[74:77], v[66:69], v[2:17]
	s_waitcnt lgkmcnt(0)
	s_barrier
; #define LAS __attribute__((address_space(3)))
; __device__ __forceinline__ float swapsum(float m) { auto rr = __builtin_amdgcn_permlane32_swap(__float_as_uint(m), __float_as_uint(m), false, false); return __uint_as_float(rr[0]) + __uint_as_float(rr[1]); }
; template <int MODE> __device__ __forceinline__ void attn_unit4(LAS unsigned char* lds, const int uidx, const AttnArgs& A) {
;     ...
;     float lt = swapsum(lsum);
;     if (MODE == 2) lt += __builtin_amdgcn_exp2f(A.sinks[2 * hx + st] * LOG2E - mref);
;     const float inv = 1.0f / lt;
; #pragma unroll
;     for (int d = 0; d < NDB; ++d)
; #pragma unroll
;         for (int r = 0; r < 16; ++r) o[d][r] *= inv;
;     const size_t orow = row0 + qslot0 + r32;
;     if (MODE == 0) {
;         LAS float* X = (LAS float*)lds;
;         if (st == 1) {
; #pragma unroll
;             for (int d = 0; d < NDB; ++d)
; #pragma unroll
;                 for (int r = 0; r < 16; ++r) X[(qg * 64 + d * 16 + r) * 64 + lane] = o[d][r];
;         }
;         __syncthreads();
	v_mfma_f32_32x32x16_bf16 v[2:17], v[244:247], v[70:73], v[2:17]
	v_mov_b32_e32 v66, v0
	s_nop 1
	v_permlane32_swap_b32_e32 v0, v66
	v_add_f32_e32 v0, v0, v66
	v_div_scale_f32 v66, s[0:1], v0, v0, 1.0
	v_rcp_f32_e32 v67, v66
	s_nop 0
	v_fma_f32 v68, -v66, v67, 1.0
	v_fmac_f32_e32 v67, v68, v67
	v_div_scale_f32 v68, vcc, 1.0, v0, 1.0
	v_mul_f32_e32 v69, v68, v67
	v_fma_f32 v70, -v66, v69, v68
	v_fmac_f32_e32 v69, v70, v67
	v_fma_f32 v66, -v66, v69, v68
	v_div_fmas_f32 v66, v66, v67, v69
	v_div_fixup_f32 v0, v66, v0, 1.0
	v_pk_mul_f32 v[88:89], v[50:51], v[0:1] op_sel_hi:[1,0]
	v_pk_mul_f32 v[90:91], v[52:53], v[0:1] op_sel_hi:[1,0]
	v_pk_mul_f32 v[84:85], v[54:55], v[0:1] op_sel_hi:[1,0]
	v_pk_mul_f32 v[86:87], v[56:57], v[0:1] op_sel_hi:[1,0]
	v_pk_mul_f32 v[80:81], v[58:59], v[0:1] op_sel_hi:[1,0]
	v_pk_mul_f32 v[82:83], v[60:61], v[0:1] op_sel_hi:[1,0]
	v_pk_mul_f32 v[76:77], v[62:63], v[0:1] op_sel_hi:[1,0]
	v_pk_mul_f32 v[78:79], v[64:65], v[0:1] op_sel_hi:[1,0]
	v_pk_mul_f32 v[72:73], v[34:35], v[0:1] op_sel_hi:[1,0]
	v_pk_mul_f32 v[74:75], v[36:37], v[0:1] op_sel_hi:[1,0]
	v_pk_mul_f32 v[68:69], v[38:39], v[0:1] op_sel_hi:[1,0]
	v_pk_mul_f32 v[70:71], v[40:41], v[0:1] op_sel_hi:[1,0]
	v_pk_mul_f32 v[64:65], v[42:43], v[0:1] op_sel_hi:[1,0]
	v_pk_mul_f32 v[66:67], v[44:45], v[0:1] op_sel_hi:[1,0]
	v_pk_mul_f32 v[60:61], v[46:47], v[0:1] op_sel_hi:[1,0]
	v_pk_mul_f32 v[62:63], v[48:49], v[0:1] op_sel_hi:[1,0]
	v_pk_mul_f32 v[48:49], v[18:19], v[0:1] op_sel_hi:[1,0]
	v_pk_mul_f32 v[54:55], v[20:21], v[0:1] op_sel_hi:[1,0]
	v_pk_mul_f32 v[38:39], v[22:23], v[0:1] op_sel_hi:[1,0]
	v_pk_mul_f32 v[40:41], v[24:25], v[0:1] op_sel_hi:[1,0]
	v_pk_mul_f32 v[34:35], v[26:27], v[0:1] op_sel_hi:[1,0]
	v_pk_mul_f32 v[36:37], v[28:29], v[0:1] op_sel_hi:[1,0]
	v_pk_mul_f32 v[26:27], v[30:31], v[0:1] op_sel_hi:[1,0]
	v_pk_mul_f32 v[30:31], v[32:33], v[0:1] op_sel_hi:[1,0]
	v_pk_mul_f32 v[24:25], v[2:3], v[0:1] op_sel_hi:[1,0]
	v_pk_mul_f32 v[28:29], v[4:5], v[0:1] op_sel_hi:[1,0]
	v_pk_mul_f32 v[20:21], v[6:7], v[0:1] op_sel_hi:[1,0]
	v_pk_mul_f32 v[22:23], v[8:9], v[0:1] op_sel_hi:[1,0]
	v_pk_mul_f32 v[18:19], v[10:11], v[0:1] op_sel_hi:[1,0]
	v_pk_mul_f32 v[12:13], v[12:13], v[0:1] op_sel_hi:[1,0]
	v_pk_mul_f32 v[10:11], v[14:15], v[0:1] op_sel_hi:[1,0]
	v_pk_mul_f32 v[2:3], v[16:17], v[0:1] op_sel_hi:[1,0]
	s_cbranch_scc1 .Lgs_pre
	s_lshl_b32 s0, s65, 14
	s_add_i32 s0, s0, 0
	v_lshl_add_u32 v0, v177, 2, s0
	ds_write2st64_b32 v0, v88, v89 offset1:1
	ds_write2st64_b32 v0, v90, v91 offset0:2 offset1:3
	ds_write2st64_b32 v0, v84, v85 offset0:4 offset1:5
	ds_write2st64_b32 v0, v86, v87 offset0:6 offset1:7
	ds_write2st64_b32 v0, v80, v81 offset0:8 offset1:9
	ds_write2st64_b32 v0, v82, v83 offset0:10 offset1:11
	ds_write2st64_b32 v0, v76, v77 offset0:12 offset1:13
	ds_write2st64_b32 v0, v78, v79 offset0:14 offset1:15
	ds_write2st64_b32 v0, v72, v73 offset0:16 offset1:17
	ds_write2st64_b32 v0, v74, v75 offset0:18 offset1:19
	ds_write2st64_b32 v0, v68, v69 offset0:20 offset1:21
	ds_write2st64_b32 v0, v70, v71 offset0:22 offset1:23
	ds_write2st64_b32 v0, v64, v65 offset0:24 offset1:25
	ds_write2st64_b32 v0, v66, v67 offset0:26 offset1:27
	ds_write2st64_b32 v0, v60, v61 offset0:28 offset1:29
	ds_write2st64_b32 v0, v62, v63 offset0:30 offset1:31
	ds_write2st64_b32 v0, v48, v49 offset0:32 offset1:33
	ds_write2st64_b32 v0, v54, v55 offset0:34 offset1:35
	ds_write2st64_b32 v0, v38, v39 offset0:36 offset1:37
	ds_write2st64_b32 v0, v40, v41 offset0:38 offset1:39
	ds_write2st64_b32 v0, v34, v35 offset0:40 offset1:41
	ds_write2st64_b32 v0, v36, v37 offset0:42 offset1:43
	ds_write2st64_b32 v0, v26, v27 offset0:44 offset1:45
	ds_write2st64_b32 v0, v30, v31 offset0:46 offset1:47
	ds_write2st64_b32 v0, v24, v25 offset0:48 offset1:49
	ds_write2st64_b32 v0, v28, v29 offset0:50 offset1:51
	ds_write2st64_b32 v0, v20, v21 offset0:52 offset1:53
	ds_write2st64_b32 v0, v22, v23 offset0:54 offset1:55
	ds_write2st64_b32 v0, v18, v19 offset0:56 offset1:57
	ds_write2st64_b32 v0, v12, v13 offset0:58 offset1:59
	ds_write2st64_b32 v0, v10, v11 offset0:60 offset1:61
	ds_write2st64_b32 v0, v2, v3 offset0:62 offset1:63

; #define GAS __attribute__((address_space(1)))
; __device__ __forceinline__ float swapsum(float m) { auto rr = __builtin_amdgcn_permlane32_swap(__float_as_uint(m), __float_as_uint(m), false, false); return __uint_as_float(rr[0]) + __uint_as_float(rr[1]); }
; __device__ __forceinline__ unsigned cvtpk(float lo, float hi) { f32x2_t v = {lo, hi}; bf16x2_t b = __builtin_convertvector(v, bf16x2_t); return __builtin_bit_cast(unsigned, b); }
; template <int MODE> __device__ __forceinline__ void attn_unit4(LAS unsigned char* lds, const int uidx, const AttnArgs& A) {
;     ...
;     __builtin_amdgcn_s_setprio(0);
;     A2_PV(vs_prev, pk);
;     __syncthreads();
;     ...
;     float lt = swapsum(lsum);
;     if (MODE == 2) lt += __builtin_amdgcn_exp2f(A.sinks[2 * hx + st] * LOG2E - mref);
;     const float inv = 1.0f / lt;
; #pragma unroll
;     for (int d = 0; d < NDB; ++d)
; #pragma unroll
;         for (int r = 0; r < 16; ++r) o[d][r] *= inv;
;     ...
;     } else {
;         GAS bf16_t* op = (GAS bf16_t*)A.O + orow * DM + (MODE == 1 ? 768 : 512) + (2 * hx + st) * 64 + 4 * hi;
; #pragma unroll
;         for (int d = 0; d < NDB; ++d)
; #pragma unroll
;             for (int g4 = 0; g4 < 4; ++g4) {
;                 u32x2 w; w.x = cvtpk(o[d][4 * g4], o[d][4 * g4 + 1]); w.y = cvtpk(o[d][4 * g4 + 2], o[d][4 * g4 + 3]);
;                 *(GAS u32x2*)(op + d * 32 + 8 * g4) = w;
;             }
;     }
;     __syncthreads();
.Lpf_m1:
	s_mov_b64 exec, s[76:77]
	v_fmac_f32_e32 v42, v143, v142
	s_setprio 0
	v_add_u32_e32 v43, 0x16800, v197
	ds_read_b64_tr_b16 v[44:45], v43
	ds_read_b64_tr_b16 v[46:47], v43 offset:2560
	ds_read_b64_tr_b16 v[244:245], v43 offset:5120
	ds_read_b64_tr_b16 v[246:247], v43 offset:7680
	s_waitcnt lgkmcnt(2)
	v_mfma_f32_32x32x16_bf16 v[18:33], v[44:47], v[50:53], v[18:33]
	ds_read_b64_tr_b16 v[44:45], v43 offset:10240
	ds_read_b64_tr_b16 v[46:47], v43 offset:12800
	s_waitcnt lgkmcnt(2)
	v_mfma_f32_32x32x16_bf16 v[18:33], v[244:247], v[54:57], v[18:33]
	ds_read_b64_tr_b16 v[244:245], v43 offset:15360
	ds_read_b64_tr_b16 v[246:247], v43 offset:17920
	s_waitcnt lgkmcnt(2)
	v_mfma_f32_32x32x16_bf16 v[18:33], v[44:47], v[34:37], v[18:33]
	ds_read_b64_tr_b16 v[44:45], v43 offset:64
	ds_read_b64_tr_b16 v[46:47], v43 offset:2624
	s_waitcnt lgkmcnt(2)
	v_mfma_f32_32x32x16_bf16 v[18:33], v[244:247], v[38:41], v[18:33]
	ds_read_b64_tr_b16 v[244:245], v43 offset:5184
	ds_read_b64_tr_b16 v[246:247], v43 offset:7744
	s_waitcnt lgkmcnt(2)
	v_mfma_f32_32x32x16_bf16 v[2:17], v[44:47], v[50:53], v[2:17]
	ds_read_b64_tr_b16 v[44:45], v43 offset:10304
	ds_read_b64_tr_b16 v[46:47], v43 offset:12864
	s_waitcnt lgkmcnt(2)
	v_mfma_f32_32x32x16_bf16 v[2:17], v[244:247], v[54:57], v[2:17]
	ds_read_b64_tr_b16 v[244:245], v43 offset:15424
	ds_read_b64_tr_b16 v[246:247], v43 offset:17984
	s_waitcnt lgkmcnt(2)
	v_mfma_f32_32x32x16_bf16 v[2:17], v[44:47], v[34:37], v[2:17]
	s_waitcnt lgkmcnt(0)
	s_barrier
	v_mfma_f32_32x32x16_bf16 v[2:17], v[244:247], v[38:41], v[2:17]
	v_mov_b32_e32 v34, v42
	s_nop 1
	v_permlane32_swap_b32_e32 v42, v34
	v_add_f32_e32 v34, v42, v34
	v_div_scale_f32 v35, s[0:1], v34, v34, 1.0
	v_rcp_f32_e32 v36, v35
	s_lshl_b32 s0, s6, 6
	s_ashr_i32 s1, s0, 31
	v_fma_f32 v37, -v35, v36, 1.0
	v_fmac_f32_e32 v36, v37, v36
	v_div_scale_f32 v37, vcc, 1.0, v34, 1.0
	v_mul_f32_e32 v38, v37, v36
	v_fma_f32 v39, -v35, v38, v37
	v_fmac_f32_e32 v38, v39, v36
	v_fma_f32 v35, -v35, v38, v37
	v_div_fmas_f32 v35, v35, v36, v38
	v_div_fixup_f32 v34, v35, v34, 1.0
	v_pk_mul_f32 v[18:19], v[18:19], v[34:35] op_sel_hi:[1,0]
	v_pk_mul_f32 v[20:21], v[20:21], v[34:35] op_sel_hi:[1,0]
	v_pk_mul_f32 v[22:23], v[22:23], v[34:35] op_sel_hi:[1,0]
	v_pk_mul_f32 v[24:25], v[24:25], v[34:35] op_sel_hi:[1,0]
	v_pk_mul_f32 v[26:27], v[26:27], v[34:35] op_sel_hi:[1,0]
	v_pk_mul_f32 v[28:29], v[28:29], v[34:35] op_sel_hi:[1,0]
	v_pk_mul_f32 v[30:31], v[30:31], v[34:35] op_sel_hi:[1,0]
	v_pk_mul_f32 v[32:33], v[32:33], v[34:35] op_sel_hi:[1,0]
	v_pk_mul_f32 v[2:3], v[2:3], v[34:35] op_sel_hi:[1,0]
	v_pk_mul_f32 v[4:5], v[4:5], v[34:35] op_sel_hi:[1,0]
	v_pk_mul_f32 v[6:7], v[6:7], v[34:35] op_sel_hi:[1,0]
	v_pk_mul_f32 v[8:9], v[8:9], v[34:35] op_sel_hi:[1,0]
	v_pk_mul_f32 v[10:11], v[10:11], v[34:35] op_sel_hi:[1,0]
	v_pk_mul_f32 v[12:13], v[12:13], v[34:35] op_sel_hi:[1,0]
	v_pk_mul_f32 v[14:15], v[14:15], v[34:35] op_sel_hi:[1,0]
	v_pk_mul_f32 v[16:17], v[16:17], v[34:35] op_sel_hi:[1,0]
	v_lshlrev_b64 v[34:35], 11, v[0:1]
	v_lshl_add_u64 v[34:35], s[10:11], 0, v[34:35]
	v_lshl_add_u64 v[34:35], s[0:1], 1, v[34:35]
	v_lshlrev_b32_e32 v0, 1, v196
	v_lshl_add_u64 v[34:35], v[34:35], 0, v[0:1]
	v_cvt_pk_bf16_f32 v18, v18, v19
	v_cvt_pk_bf16_f32 v19, v20, v21
	v_cvt_pk_bf16_f32 v2, v2, v3
	v_cvt_pk_bf16_f32 v3, v4, v5
	global_store_dwordx2 v[34:35], v[18:19], off offset:1536
	v_cvt_pk_bf16_f32 v18, v22, v23
	v_cvt_pk_bf16_f32 v19, v24, v25
	global_store_dwordx2 v[34:35], v[2:3], off offset:1600
	v_cvt_pk_bf16_f32 v2, v6, v7
	v_cvt_pk_bf16_f32 v3, v8, v9
	global_store_dwordx2 v[34:35], v[18:19], off offset:1552
	v_cvt_pk_bf16_f32 v18, v26, v27
	v_cvt_pk_bf16_f32 v19, v28, v29
	global_store_dwordx2 v[34:35], v[2:3], off offset:1616
	v_cvt_pk_bf16_f32 v2, v10, v11
	v_cvt_pk_bf16_f32 v3, v12, v13
	global_store_dwordx2 v[34:35], v[18:19], off offset:1568
	v_cvt_pk_bf16_f32 v18, v30, v31
	v_cvt_pk_bf16_f32 v19, v32, v33
	global_store_dwordx2 v[34:35], v[2:3], off offset:1632
	v_cvt_pk_bf16_f32 v2, v14, v15
	v_cvt_pk_bf16_f32 v3, v16, v17
	global_store_dwordx2 v[34:35], v[18:19], off offset:1584
	global_store_dwordx2 v[34:35], v[2:3], off offset:1648
	s_barrier
	s_cbranch_execnz .LBB0_909
	s_branch .LBB0_971
